# gMLP epilogue: y_a staged through a wave-private LDS tile and written as full 128-B lines (4 dwordx4 stores per lane instead of 8 scattered dwordx2)
# speedup vs baseline: 1.0122x; 1.0122x over previous
; __device__ __forceinline__ void gmlp_phase(const Params& p, LAS unsigned char* lds, int G) {
;     ...
;     const int j = tid >> 2, part = tid & 3;
;     const int nunits = M / 128;
;     if ((int)blockIdx.x >= nunits) return;
;     u32x4 v0, v1, v2, v3;
;     { const u32x4* src = (const u32x4*)(GV + (size_t)(blockIdx.x * 128 + j) * 512 + part * 32); v0 = src[0]; v1 = src[1]; v2 = src[2]; v3 = src[3]; }
.LBB0_649:
	s_cmpk_gt_i32 s2, 0x1ff
	v_mov_b32_e32 v0, v166
	s_cbranch_scc1 .LBB0_660
	v_and_b32_e32 v141, 63, v166
	v_lshrrev_b32_e32 v140, 6, v166
	v_mul_u32_u24_e32 v140, 0x1200, v140
	v_add_u32_e32 v140, 0x9000, v140
	v_and_b32_e32 v142, 31, v141
	v_lshrrev_b32_e32 v143, 5, v141
	v_lshrrev_b32_e32 v144, 3, v141
	v_and_b32_e32 v145, 7, v141
	v_mul_u32_u24_e32 v146, 0x90, v144
	v_lshl_add_u32 v146, v145, 4, v146
	v_add_u32_e32 v141, v140, v146
	v_mul_u32_u24_e32 v146, 0x90, v142
	v_lshl_add_u32 v146, v143, 3, v146
	v_add_u32_e32 v140, v140, v146
	v_sub_u32_e32 v146, v144, v142
	v_lshlrev_b32_e32 v146, 11, v146
	v_lshl_add_u32 v146, v145, 4, v146
	v_lshlrev_b32_e32 v147, 3, v143
	v_sub_u32_e32 v146, v146, v147
	v_add_u32_e32 v180, 0x0, v146
	v_ashrrev_i32_e32 v181, 31, v180
	v_add_u32_e32 v182, 0x4000, v146
	v_ashrrev_i32_e32 v183, 31, v182
	v_add_u32_e32 v184, 0x8000, v146
	v_ashrrev_i32_e32 v185, 31, v184
	v_add_u32_e32 v186, 0xc000, v146
	v_ashrrev_i32_e32 v187, 31, v186
	s_add_u32 s30, s92, 0x3340000
	s_addc_u32 s31, s93, 0
	s_add_u32 s0, s92, 0x10000000
	v_ashrrev_i32_e32 v81, 2, v0
	s_addc_u32 s1, s93, 0
	s_lshl_b32 s6, s2, 7
	v_add_u32_e32 v76, s6, v81
	v_mov_b32_e32 v77, 0
	v_lshlrev_b32_e32 v1, 5, v0
	v_lshlrev_b64 v[2:3], 10, v[76:77]
	v_and_b32_e32 v1, 0x60, v1
	v_lshl_add_u64 v[2:3], s[0:1], 0, v[2:3]
	v_lshlrev_b32_e32 v4, 1, v1
	v_mov_b32_e32 v5, v77
	v_lshl_add_u64 v[2:3], v[2:3], 0, v[4:5]
	global_load_dwordx4 v[32:35], v[2:3], off offset:48
	global_load_dwordx4 v[36:39], v[2:3], off offset:32
	global_load_dwordx4 v[40:43], v[2:3], off offset:16
	global_load_dwordx4 v[44:47], v[2:3], off
	v_and_b32_e32 v2, 64, v0
	v_bfe_u32 v8, v0, 5, 1
	s_movk_i32 s4, 0xffe0
	v_lshl_or_b32 v80, v8, 2, v2
	v_lshlrev_b32_e32 v2, 4, v8
	v_mov_b32_e32 v3, v77
	v_bfi_b32 v78, s4, v81, v0
	v_lshl_add_u64 v[6:7], s[92:93], 0, v[2:3]
	s_mov_b64 s[4:5], 0x2900000
	v_lshl_add_u64 v[82:83], v[6:7], 0, s[4:5]
	v_add_u32_e32 v6, 0, v2
	v_and_b32_e32 v2, 0x5f, v0
	v_mul_u32_u24_e32 v7, 0x110, v2
	v_mul_u32_u24_e32 v1, 0x110, v1
	v_lshlrev_b32_e32 v2, 1, v81
	v_ashrrev_i32_e32 v79, 31, v78
	v_and_b32_e32 v9, 31, v0
	v_add3_u32 v132, 0, v1, v2
	v_lshlrev_b64 v[2:3], 8, v[78:79]
	v_and_b32_e32 v0, 3, v0
	s_waitcnt vmcnt(15)
	v_lshl_add_u64 v[84:85], s[0:1], 0, v[4:5]
	v_lshl_add_u64 v[2:3], v[82:83], 0, v[2:3]
	s_mov_b64 s[0:1], 0x18000
	v_lshlrev_b32_e32 v0, 6, v0
	v_mov_b32_e32 v1, v77
	v_and_b32_e32 v10, 0xffffffe0, v81
	v_lshl_add_u64 v[86:87], v[2:3], 0, s[0:1]
	v_lshlrev_b32_e32 v2, 2, v80
	v_mov_b32_e32 v3, v77
	s_waitcnt vmcnt(13)
	v_lshl_add_u64 v[92:93], s[92:93], 0, v[0:1]
	v_lshlrev_b32_e32 v0, 1, v80
	v_lshl_add_u64 v[90:91], s[56:57], 0, v[2:3]
	v_lshl_add_u64 v[94:95], s[92:93], 0, v[0:1]
	v_add_u32_e32 v0, s6, v10
	s_mov_b64 s[0:1], 0xe0
	v_cmp_eq_u32_e64 s[38:39], 0, v8
	v_lshl_add_u64 v[88:89], v[78:79], 2, s[60:61]
	s_lshl_b32 s4, s3, 7
	s_waitcnt vmcnt(12)
	v_or_b32_e32 v96, v0, v9
	v_lshl_add_u64 v[98:99], v[90:91], 0, s[0:1]
	v_mov_b32_e32 v79, 0x358637bd
	s_mov_b32 s5, 0xf800000
	v_mov_b32_e32 v133, 0x260
	v_add_u32_e32 v134, v6, v7
	v_mov_b32_e32 v100, v76
	s_mov_b32 s6, s2
	s_branch .LBB0_652

; __device__ __forceinline__ unsigned cvt_pk(float lo, float hi) { unsigned r; asm volatile("v_cvt_pk_bf16_f32 %0, %1, %2" : "=v"(r) : "v"(lo), "v"(hi)); return r; }
; __device__ __forceinline__ void gmlp_phase(const Params& p, LAS unsigned char* lds, int G) {
;     ...
;             const int i = 32 * wi + l32; const size_t tok = (size_t)(row0 + i);
;             const int cb = g * 128 + 64 * wc + 4 * hi;
;             const bf16_t* ap = WSM + (size_t)(g * 128 + i) * 128 + 8 * hi;
;             bf16x8 wf[8]; u32x2 guv[8];
; #pragma unroll
;             for (int ks = 0; ks < 8; ++ks) wf[ks] = *(const bf16x8*)(ap + 16 * ks);
; #pragma unroll
;             for (int q = 0; q < 4; ++q) { guv[2 * q] = *(const u32x2*)(GU + tok * 512 + cb + 8 * q); guv[2 * q + 1] = *(const u32x2*)(GU + tok * 512 + cb + 32 + 8 * q); }
;             const float bi = bs[g * 128 + i];
;             {
;                 float f[32];
;                 f[0] = bflo(v0.x); f[1] = bfhi(v0.x); f[2] = bflo(v0.y); f[3] = bfhi(v0.y); f[4] = bflo(v0.z); f[5] = bfhi(v0.z); f[6] = bflo(v0.w); f[7] = bfhi(v0.w);
;                 f[8] = bflo(v1.x); f[9] = bfhi(v1.x); f[10] = bflo(v1.y); f[11] = bfhi(v1.y); f[12] = bflo(v1.z); f[13] = bfhi(v1.z); f[14] = bflo(v1.w); f[15] = bfhi(v1.w);
;                 f[16] = bflo(v2.x); f[17] = bfhi(v2.x); f[18] = bflo(v2.y); f[19] = bfhi(v2.y); f[20] = bflo(v2.z); f[21] = bfhi(v2.z); f[22] = bflo(v2.w); f[23] = bfhi(v2.w);
;                 f[24] = bflo(v3.x); f[25] = bfhi(v3.x); f[26] = bflo(v3.y); f[27] = bfhi(v3.y); f[28] = bflo(v3.z); f[29] = bfhi(v3.z); f[30] = bflo(v3.w); f[31] = bfhi(v3.w);
;                 float ss = 0.f;
; #pragma unroll
;                 for (int e = 0; e < 32; ++e) ss += f[e] * f[e];
;                 ss += __shfl_xor(ss, 1); ss += __shfl_xor(ss, 2);
;                 const float r = 1.0f / sqrtf(ss * (1.f / 128.f) + EPS);
; #pragma unroll
;                 for (int e = 0; e < 32; e += 2) { const unsigned w = cvt_pk(f[e] * r, f[e + 1] * r);
;                     vT[(part * 32 + e) * 136 + j] = (bf16_t)(w & 0xffffu); vT[(part * 32 + e + 1) * 136 + j] = (bf16_t)(w >> 16); }
.LBB0_654:
	s_waitcnt vmcnt(0)
	v_and_b32_e32 v7, 0xffff0000, v44
	v_lshlrev_b32_e32 v6, 16, v44
	v_lshlrev_b32_e32 v26, 16, v38
	v_and_b32_e32 v27, 0xffff0000, v38
	v_mul_f32_e32 v38, v7, v7
	v_lshlrev_b32_e32 v8, 16, v45
	v_fmac_f32_e32 v38, v6, v6
	v_and_b32_e32 v9, 0xffff0000, v45
	v_fmac_f32_e32 v38, v8, v8
	v_lshlrev_b32_e32 v10, 16, v46
	v_fmac_f32_e32 v38, v9, v9
	v_and_b32_e32 v11, 0xffff0000, v46
	v_fmac_f32_e32 v38, v10, v10
	v_lshlrev_b32_e32 v12, 16, v47
	v_fmac_f32_e32 v38, v11, v11
	v_and_b32_e32 v13, 0xffff0000, v47
	v_fmac_f32_e32 v38, v12, v12
	v_lshlrev_b32_e32 v14, 16, v40
	v_fmac_f32_e32 v38, v13, v13
	v_and_b32_e32 v15, 0xffff0000, v40
	v_fmac_f32_e32 v38, v14, v14
	v_lshlrev_b32_e32 v16, 16, v41
	v_fmac_f32_e32 v38, v15, v15
	v_and_b32_e32 v17, 0xffff0000, v41
	v_fmac_f32_e32 v38, v16, v16
	v_lshlrev_b32_e32 v18, 16, v42
	v_fmac_f32_e32 v38, v17, v17
	v_and_b32_e32 v19, 0xffff0000, v42
	v_fmac_f32_e32 v38, v18, v18
	v_lshlrev_b32_e32 v20, 16, v43
	v_fmac_f32_e32 v38, v19, v19
	v_and_b32_e32 v21, 0xffff0000, v43
	v_fmac_f32_e32 v38, v20, v20
	v_lshlrev_b32_e32 v22, 16, v36
	v_fmac_f32_e32 v38, v21, v21
	v_and_b32_e32 v23, 0xffff0000, v36
	v_fmac_f32_e32 v38, v22, v22
	v_lshlrev_b32_e32 v24, 16, v37
	v_fmac_f32_e32 v38, v23, v23
	v_and_b32_e32 v25, 0xffff0000, v37
	v_fmac_f32_e32 v38, v24, v24
	v_fmac_f32_e32 v38, v25, v25
	v_fmac_f32_e32 v38, v26, v26
	v_lshlrev_b32_e32 v28, 16, v39
	v_fmac_f32_e32 v38, v27, v27
	v_and_b32_e32 v29, 0xffff0000, v39
	v_fmac_f32_e32 v38, v28, v28
	v_lshlrev_b32_e32 v30, 16, v32
	v_fmac_f32_e32 v38, v29, v29
	v_and_b32_e32 v31, 0xffff0000, v32
	v_fmac_f32_e32 v38, v30, v30
	v_lshlrev_b32_e32 v32, 16, v33
	v_fmac_f32_e32 v38, v31, v31
	v_and_b32_e32 v33, 0xffff0000, v33
	v_fmac_f32_e32 v38, v32, v32
	v_lshlrev_b32_e32 v36, 16, v34
	v_fmac_f32_e32 v38, v33, v33
	v_and_b32_e32 v34, 0xffff0000, v34
	v_fmac_f32_e32 v38, v36, v36
	v_lshlrev_b32_e32 v37, 16, v35
	v_fmac_f32_e32 v38, v34, v34
	v_and_b32_e32 v35, 0xffff0000, v35
	v_fmac_f32_e32 v38, v37, v37
	v_fmac_f32_e32 v38, v35, v35
	ds_bpermute_b32 v39, v167, v38
	v_ashrrev_i32_e32 v113, 31, v112
	v_lshlrev_b64 v[0:1], 8, v[112:113]
	v_lshl_add_u64 v[4:5], v[82:83], 0, v[0:1]
	global_load_dwordx4 v[0:3], v[4:5], off
	global_load_dwordx4 v[72:75], v[4:5], off offset:32
	global_load_dwordx4 v[68:71], v[4:5], off offset:64
	global_load_dwordx4 v[64:67], v[4:5], off offset:96
	global_load_dwordx4 v[60:63], v[4:5], off offset:128
	global_load_dwordx4 v[56:59], v[4:5], off offset:160
	global_load_dwordx4 v[52:55], v[4:5], off offset:192
	global_load_dwordx4 v[48:51], v[4:5], off offset:224
	s_waitcnt lgkmcnt(0)
	v_add_f32_e32 v38, v38, v39
	ds_bpermute_b32 v39, v168, v38
	v_lshl_add_u64 v[4:5], v[108:109], 0, s[34:35]
	s_brev_b32 s0, 48
	v_add_co_u32_e32 v4, vcc, s0, v4
	s_waitcnt lgkmcnt(0)
	v_add_f32_e32 v38, v38, v39
	v_addc_co_u32_e32 v5, vcc, 0, v5, vcc
	v_fmamk_f32 v38, v38, 0x3c000000, v79
	v_cmp_gt_f32_e32 vcc, s5, v38
	v_mul_f32_e32 v39, 0x4f800000, v38
	global_load_dwordx2 v[130:131], v[4:5], off
	global_load_dwordx2 v[128:129], v[4:5], off offset:64
	global_load_dwordx2 v[126:127], v[4:5], off offset:16
	global_load_dwordx2 v[124:125], v[4:5], off offset:80
	v_cndmask_b32_e32 v38, v38, v39, vcc
	v_sqrt_f32_e32 v39, v38
	global_load_dwordx2 v[122:123], v[4:5], off offset:32
	global_load_dwordx2 v[120:121], v[4:5], off offset:96
	global_load_dwordx2 v[118:119], v[4:5], off offset:48
	global_load_dwordx2 v[116:117], v[4:5], off offset:112
	v_lshl_add_u64 v[4:5], v[112:113], 2, s[60:61]
	v_add_u32_e32 v40, -1, v39
	v_fma_f32 v41, -v40, v39, v38
	v_cmp_ge_f32_e64 s[0:1], 0, v41
	v_add_u32_e32 v41, 1, v39
	global_load_dword v76, v[4:5], off
	v_cndmask_b32_e64 v40, v39, v40, s[0:1]
	v_fma_f32 v39, -v41, v39, v38
	v_cmp_lt_f32_e64 s[0:1], 0, v39
	s_nop 1
	v_cndmask_b32_e64 v39, v40, v41, s[0:1]
	v_mul_f32_e32 v40, 0x37800000, v39
	v_cndmask_b32_e32 v39, v39, v40, vcc
	v_cmp_class_f32_e32 vcc, v38, v133
	s_nop 1
	v_cndmask_b32_e32 v38, v39, v38, vcc
	v_div_scale_f32 v39, s[0:1], v38, v38, 1.0
	v_rcp_f32_e32 v40, v39
	s_mov_b64 s[0:1], 0x10000100
	v_fma_f32 v4, -v39, v40, 1.0
	v_fmac_f32_e32 v40, v4, v40
	v_div_scale_f32 v4, vcc, 1.0, v38, 1.0
	v_mul_f32_e32 v5, v4, v40
	v_fma_f32 v41, -v39, v5, v4
	v_fmac_f32_e32 v5, v41, v40
	v_fma_f32 v4, -v39, v5, v4
	v_div_fmas_f32 v4, v4, v40, v5
	v_div_fixup_f32 v4, v4, v38, 1.0
	v_mul_f32_e32 v5, v4, v6
	v_mul_f32_e32 v6, v4, v7
	v_cvt_pk_bf16_f32 v5, v5, v6
	ds_write_b16 v132, v5
	ds_write_b16_d16_hi v132, v5 offset:272
	v_mul_f32_e32 v5, v4, v8
	v_mul_f32_e32 v6, v4, v9
	v_cvt_pk_bf16_f32 v5, v5, v6
	ds_write_b16 v132, v5 offset:544
	ds_write_b16_d16_hi v132, v5 offset:816
	v_mul_f32_e32 v5, v4, v10
	v_mul_f32_e32 v6, v4, v11
	v_cvt_pk_bf16_f32 v5, v5, v6
	ds_write_b16 v132, v5 offset:1088
	ds_write_b16_d16_hi v132, v5 offset:1360
	v_mul_f32_e32 v5, v4, v12
	v_mul_f32_e32 v6, v4, v13
	v_cvt_pk_bf16_f32 v5, v5, v6
	ds_write_b16 v132, v5 offset:1632
	ds_write_b16_d16_hi v132, v5 offset:1904
	v_mul_f32_e32 v5, v4, v14
	v_mul_f32_e32 v6, v4, v15
	v_cvt_pk_bf16_f32 v5, v5, v6
	ds_write_b16 v132, v5 offset:2176
	ds_write_b16_d16_hi v132, v5 offset:2448
	v_mul_f32_e32 v5, v4, v16
	v_mul_f32_e32 v6, v4, v17
	v_cvt_pk_bf16_f32 v5, v5, v6
	ds_write_b16 v132, v5 offset:2720
	ds_write_b16_d16_hi v132, v5 offset:2992
	v_mul_f32_e32 v5, v4, v18
	v_mul_f32_e32 v6, v4, v19
	v_cvt_pk_bf16_f32 v5, v5, v6
	ds_write_b16 v132, v5 offset:3264
	ds_write_b16_d16_hi v132, v5 offset:3536
	v_mul_f32_e32 v5, v4, v20
	v_mul_f32_e32 v6, v4, v21
	v_cvt_pk_bf16_f32 v5, v5, v6
	ds_write_b16 v132, v5 offset:3808
; #define LAS __attribute__((address_space(3)))
; __device__ __forceinline__ void gmlp_phase(const Params& p, LAS unsigned char* lds, int G) {
;     ...
;                 for (int e = 0; e < 32; e += 2) { const unsigned w = cvt_pk(f[e] * r, f[e + 1] * r);
;                     vT[(part * 32 + e) * 136 + j] = (bf16_t)(w & 0xffffu); vT[(part * 32 + e + 1) * 136 + j] = (bf16_t)(w >> 16); }
;             }
;             {
;                 const int gn = (g + 1) & 3, un = (g == 3) ? unit + G : unit;
;                 if (un < nunits) { const u32x4* src = (const u32x4*)(GV + (size_t)(un * 128 + j) * 512 + gn * 128 + part * 32); v0 = src[0]; v1 = src[1]; v2 = src[2]; v3 = src[3]; }
;             }
;             __syncthreads();
;             f32x16 acc0, acc1;
; #pragma unroll
;             for (int e = 0; e < 16; ++e) { acc0[e] = 0.f; acc1[e] = 0.f; }
;             const LAS bf16_t* bp0 = vT + (64 * wc + l32) * 136 + 8 * hi; const LAS bf16_t* bp1 = bp0 + 32 * 136;
; #pragma unroll
;             for (int ks = 0; ks < 8; ++ks) {
;                 const bf16x8 b0 = *(const LAS bf16x8*)(bp0 + 16 * ks), b1 = *(const LAS bf16x8*)(bp1 + 16 * ks);
;                 acc0 = __builtin_amdgcn_mfma_f32_32x32x16_bf16(b0, wf[ks], acc0, 0, 0, 0);
;                 acc1 = __builtin_amdgcn_mfma_f32_32x32x16_bf16(b1, wf[ks], acc1, 0, 0, 0);
;             }
;             float yss = 0.f;
; #pragma unroll
;             for (int q = 0; q < 4; ++q) {
; #pragma unroll
;                 for (int hb = 0; hb < 2; ++hb) {
;                     const int c = cb + 32 * hb + 8 * q;
;                     const u32x2 gu = guv[2 * q + hb]; const f32x4 gv = *(const f32x4*)(gvn + c);
;                     const float a0 = hb ? acc1[4 * q] : acc0[4 * q], a1 = hb ? acc1[4 * q + 1] : acc0[4 * q + 1], a2 = hb ? acc1[4 * q + 2] : acc0[4 * q + 2], a3 = hb ? acc1[4 * q + 3] : acc0[4 * q + 3];
;                     const float y0 = bflo(gu.x) * (gv.x * a0 + bi), y1 = bfhi(gu.x) * (gv.y * a1 + bi), y2 = bflo(gu.y) * (gv.z * a2 + bi), y3 = bfhi(gu.y) * (gv.w * a3 + bi);
;                     yss += (y0 * y0 + y1 * y1) + (y2 * y2 + y3 * y3);
;                     u32x2 o; o.x = cvt_pk(y0, y1); o.y = cvt_pk(y2, y3);
;                     *(u32x2*)(Y + tok * 1024 + c) = o;
	ds_write_b16_d16_hi v132, v5 offset:4080
	v_mul_f32_e32 v5, v4, v22
	v_mul_f32_e32 v6, v4, v23
	v_cvt_pk_bf16_f32 v5, v5, v6
	ds_write_b16 v132, v5 offset:4352
	ds_write_b16_d16_hi v132, v5 offset:4624
	v_mul_f32_e32 v5, v4, v24
	v_mul_f32_e32 v6, v4, v25
	v_cvt_pk_bf16_f32 v5, v5, v6
	ds_write_b16 v132, v5 offset:4896
	ds_write_b16_d16_hi v132, v5 offset:5168
	v_mul_f32_e32 v5, v4, v26
	v_mul_f32_e32 v6, v4, v27
	v_cvt_pk_bf16_f32 v5, v5, v6
	ds_write_b16 v132, v5 offset:5440
	ds_write_b16_d16_hi v132, v5 offset:5712
	v_mul_f32_e32 v5, v4, v28
	v_mul_f32_e32 v6, v4, v29
	v_cvt_pk_bf16_f32 v5, v5, v6
	ds_write_b16 v132, v5 offset:5984
	ds_write_b16_d16_hi v132, v5 offset:6256
	v_mul_f32_e32 v5, v4, v30
	v_mul_f32_e32 v6, v4, v31
	v_cvt_pk_bf16_f32 v5, v5, v6
	ds_write_b16 v132, v5 offset:6528
	ds_write_b16_d16_hi v132, v5 offset:6800
	v_mul_f32_e32 v5, v4, v32
	v_mul_f32_e32 v6, v4, v33
	v_cvt_pk_bf16_f32 v5, v5, v6
	ds_write_b16 v132, v5 offset:7072
	ds_write_b16_d16_hi v132, v5 offset:7344
	v_mul_f32_e32 v5, v4, v36
	v_mul_f32_e32 v6, v4, v34
	v_cvt_pk_bf16_f32 v5, v5, v6
	ds_write_b16 v132, v5 offset:7616
	ds_write_b16_d16_hi v132, v5 offset:7888
	v_mul_f32_e32 v5, v4, v37
	v_mul_f32_e32 v4, v4, v35
	v_cvt_pk_bf16_f32 v4, v5, v4
	ds_write_b16 v132, v4 offset:8160
	ds_write_b16_d16_hi v132, v4 offset:8432
	v_lshl_add_u64 v[4:5], v[106:107], 0, s[34:35]
	v_lshl_add_u64 v[6:7], v[4:5], 0, s[0:1]
	s_brev_b32 s0, 8
	v_add_co_u32_e32 v4, vcc, s0, v4
	s_brev_b32 s0, 20
	s_nop 0
	v_addc_co_u32_e32 v5, vcc, 0, v5, vcc
	global_load_dwordx4 v[44:47], v[4:5], off offset:256
	global_load_dwordx4 v[32:35], v[6:7], off offset:48
	global_load_dwordx4 v[36:39], v[6:7], off offset:32
	global_load_dwordx4 v[40:43], v[6:7], off offset:16
	s_waitcnt lgkmcnt(0)
	s_barrier
	ds_read_b128 v[4:7], v134
	ds_read_b128 v[136:139], v134 offset:32
	s_waitcnt vmcnt(20) lgkmcnt(1)
	v_mfma_f32_32x32x16_bf16 v[16:31], v[4:7], v[0:3], 0
	ds_read_b128 v[4:7], v134 offset:8704
	s_waitcnt vmcnt(19) lgkmcnt(1)
	v_mfma_f32_32x32x16_bf16 v[16:31], v[136:139], v[72:75], v[16:31]
	ds_read_b128 v[136:139], v134 offset:8736
	s_waitcnt lgkmcnt(1)
	v_mfma_f32_32x32x16_bf16 v[0:15], v[4:7], v[0:3], 0
	s_waitcnt lgkmcnt(0)
	v_mfma_f32_32x32x16_bf16 v[0:15], v[136:139], v[72:75], v[0:15]
	ds_read_b128 v[72:75], v134 offset:64
	s_waitcnt vmcnt(18) lgkmcnt(0)
	v_mfma_f32_32x32x16_bf16 v[16:31], v[72:75], v[68:71], v[16:31]
	ds_read_b128 v[72:75], v134 offset:8768
	s_waitcnt lgkmcnt(0)
	v_mfma_f32_32x32x16_bf16 v[0:15], v[72:75], v[68:71], v[0:15]
	ds_read_b128 v[68:71], v134 offset:96
	global_load_dwordx4 v[72:75], v[114:115], off offset:-224
	s_waitcnt vmcnt(18) lgkmcnt(0)
	v_mfma_f32_32x32x16_bf16 v[16:31], v[68:71], v[64:67], v[16:31]
	ds_read_b128 v[68:71], v134 offset:8800
	s_waitcnt lgkmcnt(0)
	v_mfma_f32_32x32x16_bf16 v[0:15], v[68:71], v[64:67], v[0:15]
	ds_read_b128 v[64:67], v134 offset:128
	s_waitcnt vmcnt(17) lgkmcnt(0)
	v_mfma_f32_32x32x16_bf16 v[16:31], v[64:67], v[60:63], v[16:31]
	ds_read_b128 v[64:67], v134 offset:8832
	s_waitcnt lgkmcnt(0)
	v_mfma_f32_32x32x16_bf16 v[0:15], v[64:67], v[60:63], v[0:15]
	ds_read_b128 v[60:63], v134 offset:160
	s_waitcnt vmcnt(16) lgkmcnt(0)
	v_mfma_f32_32x32x16_bf16 v[16:31], v[60:63], v[56:59], v[16:31]
	ds_read_b128 v[60:63], v134 offset:8864
	s_waitcnt lgkmcnt(0)
	v_mfma_f32_32x32x16_bf16 v[0:15], v[60:63], v[56:59], v[0:15]
	ds_read_b128 v[56:59], v134 offset:192
	s_waitcnt vmcnt(15) lgkmcnt(0)
	v_mfma_f32_32x32x16_bf16 v[16:31], v[56:59], v[52:55], v[16:31]
	ds_read_b128 v[56:59], v134 offset:8896
	s_waitcnt lgkmcnt(0)
	v_mfma_f32_32x32x16_bf16 v[0:15], v[56:59], v[52:55], v[0:15]
	ds_read_b128 v[52:55], v134 offset:224
	ds_read_b128 v[56:59], v134 offset:8928
	s_waitcnt vmcnt(14) lgkmcnt(1)
	v_mfma_f32_32x32x16_bf16 v[16:31], v[52:55], v[48:51], v[16:31]
	s_waitcnt vmcnt(13)
	v_lshlrev_b32_e32 v52, 16, v130
	s_waitcnt lgkmcnt(0)
	v_mfma_f32_32x32x16_bf16 v[0:15], v[56:59], v[48:51], v[0:15]
	s_waitcnt vmcnt(0)
	s_nop 6
	v_fma_f32 v16, v16, v72, v76
	v_mul_f32_e32 v60, v16, v52
	v_and_b32_e32 v16, 0xffff0000, v130
	v_fma_f32 v17, v17, v73, v76
	v_mul_f32_e32 v61, v17, v16
	v_lshlrev_b32_e32 v16, 16, v131
	v_fma_f32 v17, v18, v74, v76
	v_mul_f32_e32 v62, v17, v16
	v_and_b32_e32 v16, 0xffff0000, v131
	v_fma_f32 v17, v19, v75, v76
	v_mul_f32_e32 v63, v17, v16
	v_lshl_add_u64 v[16:17], v[110:111], 0, s[34:35]
	v_add_co_u32_e32 v16, vcc, s0, v16
	v_cvt_pk_bf16_f32 v18, v60, v61
	v_cvt_pk_bf16_f32 v19, v62, v63
	v_lshlrev_b32_e32 v50, 16, v126
	s_nop 0
	v_addc_co_u32_e32 v17, vcc, 0, v17, vcc
	ds_write_b64 v140, v[18:19] offset:0
	global_load_dwordx4 v[52:55], v[114:115], off offset:-96
	v_lshlrev_b32_e32 v18, 16, v128
	v_and_b32_e32 v51, 0xffff0000, v126
	s_waitcnt vmcnt(0)
	v_fma_f32 v0, v0, v52, v76
	v_mul_f32_e32 v18, v0, v18
	v_and_b32_e32 v0, 0xffff0000, v128
	v_fma_f32 v1, v1, v53, v76
	v_mul_f32_e32 v19, v1, v0
	v_lshlrev_b32_e32 v0, 16, v129
	v_fma_f32 v1, v2, v54, v76
	v_mul_f32_e32 v48, v1, v0
	v_and_b32_e32 v0, 0xffff0000, v129
	v_fma_f32 v1, v3, v55, v76
	v_mul_f32_e32 v49, v1, v0
	v_cvt_pk_bf16_f32 v0, v18, v19
	v_cvt_pk_bf16_f32 v1, v48, v49
	ds_write_b64 v140, v[0:1] offset:64
	global_load_dwordx4 v[0:3], v[114:115], off offset:-192
	v_lshlrev_b32_e32 v52, 16, v127
	v_and_b32_e32 v53, 0xffff0000, v127
	v_mul_f32_e32 v19, v19, v19
	v_mul_f32_e32 v49, v49, v49
	v_mul_f32_e32 v54, v61, v61
	v_mul_f32_e32 v55, v63, v63
	v_fmac_f32_e32 v19, v18, v18
	v_fmac_f32_e32 v49, v48, v48
	v_fmac_f32_e32 v54, v60, v60
	v_fmac_f32_e32 v55, v62, v62
	v_add_f32_e32 v18, v19, v49
	v_add_f32_e32 v54, v54, v55
	v_add_f32_e32 v18, v54, v18
	s_waitcnt vmcnt(0)
; __device__ __forceinline__ unsigned cvt_pk(float lo, float hi) { unsigned r; asm volatile("v_cvt_pk_bf16_f32 %0, %1, %2" : "=v"(r) : "v"(lo), "v"(hi)); return r; }
; __device__ __forceinline__ void gmlp_phase(const Params& p, LAS unsigned char* lds, int G) {
;     ...
;             float yss = 0.f;
; #pragma unroll
;             for (int q = 0; q < 4; ++q) {
; #pragma unroll
;                 for (int hb = 0; hb < 2; ++hb) {
;                     const int c = cb + 32 * hb + 8 * q;
;                     const u32x2 gu = guv[2 * q + hb]; const f32x4 gv = *(const f32x4*)(gvn + c);
;                     const float a0 = hb ? acc1[4 * q] : acc0[4 * q], a1 = hb ? acc1[4 * q + 1] : acc0[4 * q + 1], a2 = hb ? acc1[4 * q + 2] : acc0[4 * q + 2], a3 = hb ? acc1[4 * q + 3] : acc0[4 * q + 3];
;                     const float y0 = bflo(gu.x) * (gv.x * a0 + bi), y1 = bfhi(gu.x) * (gv.y * a1 + bi), y2 = bflo(gu.y) * (gv.z * a2 + bi), y3 = bfhi(gu.y) * (gv.w * a3 + bi);
;                     yss += (y0 * y0 + y1 * y1) + (y2 * y2 + y3 * y3);
;                     u32x2 o; o.x = cvt_pk(y0, y1); o.y = cvt_pk(y2, y3);
;                     *(u32x2*)(Y + tok * 1024 + c) = o;
;                 }
;             }
;             yss += __shfl_xor(yss, 32);
;             if (hi == 0) unsafeAtomicAdd(SSA + tok, yss);
	v_fma_f32 v0, v20, v0, v76
	v_fma_f32 v1, v21, v1, v76
	v_fma_f32 v2, v22, v2, v76
	v_fma_f32 v3, v23, v3, v76
	v_mul_f32_e32 v20, v0, v50
	v_mul_f32_e32 v21, v1, v51
	v_mul_f32_e32 v22, v2, v52
	v_mul_f32_e32 v23, v3, v53
	v_cvt_pk_bf16_f32 v0, v20, v21
	v_cvt_pk_bf16_f32 v1, v22, v23
	ds_write_b64 v140, v[0:1] offset:16
	global_load_dwordx4 v[0:3], v[114:115], off offset:-64
	v_lshlrev_b32_e32 v50, 16, v124
	v_and_b32_e32 v51, 0xffff0000, v124
	v_lshlrev_b32_e32 v52, 16, v125
	v_and_b32_e32 v53, 0xffff0000, v125
	v_mul_f32_e32 v19, v21, v21
	v_mul_f32_e32 v21, v23, v23
	v_fmac_f32_e32 v19, v20, v20
	v_fmac_f32_e32 v21, v22, v22
	v_add_f32_e32 v19, v19, v21
	v_add_f32_e32 v18, v18, v19
	s_waitcnt vmcnt(0)
	v_fma_f32 v0, v4, v0, v76
	v_fma_f32 v1, v5, v1, v76
	v_fma_f32 v2, v6, v2, v76
	v_fma_f32 v3, v7, v3, v76
	v_mul_f32_e32 v4, v0, v50
	v_mul_f32_e32 v5, v1, v51
	v_mul_f32_e32 v6, v2, v52
	v_mul_f32_e32 v7, v3, v53
	v_cvt_pk_bf16_f32 v0, v4, v5
	v_cvt_pk_bf16_f32 v1, v6, v7
	ds_write_b64 v140, v[0:1] offset:80
	global_load_dwordx4 v[0:3], v[114:115], off offset:-160
	v_lshlrev_b32_e32 v50, 16, v122
	v_and_b32_e32 v51, 0xffff0000, v122
	v_lshlrev_b32_e32 v52, 16, v123
	v_and_b32_e32 v53, 0xffff0000, v123
	v_mul_f32_e32 v5, v5, v5
	v_mul_f32_e32 v7, v7, v7
	v_fmac_f32_e32 v5, v4, v4
	v_fmac_f32_e32 v7, v6, v6
	v_add_f32_e32 v4, v5, v7
	v_add_f32_e32 v4, v18, v4
	s_waitcnt vmcnt(0)
	v_fma_f32 v0, v24, v0, v76
	v_fma_f32 v1, v25, v1, v76
	v_fma_f32 v2, v26, v2, v76
	v_fma_f32 v3, v27, v3, v76
	v_mul_f32_e32 v24, v0, v50
	v_mul_f32_e32 v25, v1, v51
	v_mul_f32_e32 v26, v2, v52
	v_mul_f32_e32 v27, v3, v53
	v_cvt_pk_bf16_f32 v0, v24, v25
	v_cvt_pk_bf16_f32 v1, v26, v27
	ds_write_b64 v140, v[0:1] offset:32
	global_load_dwordx4 v[0:3], v[114:115], off offset:-32
	v_lshlrev_b32_e32 v50, 16, v120
	v_and_b32_e32 v51, 0xffff0000, v120
	v_lshlrev_b32_e32 v52, 16, v121
	v_and_b32_e32 v53, 0xffff0000, v121
	v_mul_f32_e32 v5, v25, v25
	v_mul_f32_e32 v6, v27, v27
	v_fmac_f32_e32 v5, v24, v24
	v_fmac_f32_e32 v6, v26, v26
	v_add_f32_e32 v5, v5, v6
	v_add_f32_e32 v4, v4, v5
	s_waitcnt vmcnt(0)
	v_fma_f32 v0, v8, v0, v76
	v_fma_f32 v1, v9, v1, v76
	v_fma_f32 v2, v10, v2, v76
	v_fma_f32 v3, v11, v3, v76
	v_mul_f32_e32 v8, v0, v50
	v_mul_f32_e32 v9, v1, v51
	v_mul_f32_e32 v10, v2, v52
	v_mul_f32_e32 v11, v3, v53
	v_cvt_pk_bf16_f32 v0, v8, v9
	v_cvt_pk_bf16_f32 v1, v10, v11
	ds_write_b64 v140, v[0:1] offset:96
	global_load_dwordx4 v[0:3], v[114:115], off offset:-128
	v_lshlrev_b32_e32 v50, 16, v118
	v_and_b32_e32 v51, 0xffff0000, v118
	v_lshlrev_b32_e32 v52, 16, v119
	v_and_b32_e32 v53, 0xffff0000, v119
	v_mul_f32_e32 v5, v9, v9
	v_mul_f32_e32 v6, v11, v11
	v_fmac_f32_e32 v5, v8, v8
	v_fmac_f32_e32 v6, v10, v10
	v_add_f32_e32 v5, v5, v6
	v_add_f32_e32 v4, v4, v5
	s_waitcnt vmcnt(0)
	v_fma_f32 v0, v28, v0, v76
	v_fma_f32 v1, v29, v1, v76
	v_fma_f32 v2, v30, v2, v76
	v_fma_f32 v3, v31, v3, v76
	v_mul_f32_e32 v28, v0, v50
	v_mul_f32_e32 v29, v1, v51
	v_mul_f32_e32 v30, v2, v52
	v_mul_f32_e32 v31, v3, v53
	v_cvt_pk_bf16_f32 v0, v28, v29
	v_cvt_pk_bf16_f32 v1, v30, v31
	ds_write_b64 v140, v[0:1] offset:48
	global_load_dwordx4 v[0:3], v[114:115], off
	v_mul_f32_e32 v5, v29, v29
	v_mul_f32_e32 v6, v31, v31
	v_fmac_f32_e32 v5, v28, v28
	v_fmac_f32_e32 v6, v30, v30
	v_and_b32_e32 v51, 0xffff0000, v116
	v_and_b32_e32 v53, 0xffff0000, v117
	v_add_f32_e32 v5, v5, v6
	v_lshlrev_b32_e32 v50, 16, v116
	v_lshlrev_b32_e32 v52, 16, v117
	v_add_f32_e32 v4, v4, v5
	s_waitcnt vmcnt(0)
	v_fma_f32 v0, v12, v0, v76
	v_fma_f32 v1, v13, v1, v76
	v_fma_f32 v2, v14, v2, v76
	v_fmac_f32_e32 v76, v15, v3
	v_mul_f32_e32 v5, v1, v51
	v_mul_f32_e32 v7, v76, v53
	v_mul_f32_e32 v3, v0, v50
	v_mul_f32_e32 v6, v2, v52
	v_mul_f32_e32 v0, v5, v5
	v_mul_f32_e32 v1, v7, v7
	v_fmac_f32_e32 v0, v3, v3
	v_fmac_f32_e32 v1, v6, v6
	v_add_f32_e32 v0, v0, v1
	v_add_f32_e32 v0, v4, v0
	ds_bpermute_b32 v1, v169, v0
	v_cvt_pk_bf16_f32 v2, v3, v5
	v_cvt_pk_bf16_f32 v3, v6, v7
	ds_write_b64 v140, v[2:3] offset:112
	s_waitcnt lgkmcnt(0)
	ds_read_b128 v[148:151], v141 offset:0
	ds_read_b128 v[152:155], v141 offset:1152
	ds_read_b128 v[156:159], v141 offset:2304
	ds_read_b128 v[160:163], v141 offset:3456
	v_lshl_add_u64 v[164:165], v[16:17], 0, v[180:181]
	v_lshl_add_u64 v[170:171], v[16:17], 0, v[182:183]
	v_lshl_add_u64 v[172:173], v[16:17], 0, v[184:185]
	v_lshl_add_u64 v[174:175], v[16:17], 0, v[186:187]
	s_waitcnt lgkmcnt(0)
	global_store_dwordx4 v[164:165], v[148:151], off
	global_store_dwordx4 v[170:171], v[152:155], off
	global_store_dwordx4 v[172:173], v[156:159], off
	global_store_dwordx4 v[174:175], v[160:163], off
	s_and_saveexec_b64 s[0:1], s[38:39]
	s_cbranch_execz .LBB0_653
	s_waitcnt lgkmcnt(0)
	v_add_f32_e32 v0, v0, v1
	global_atomic_add_f32 v[102:103], v0, off
	s_branch .LBB0_653

; #define LAS __attribute__((address_space(3)))
; __device__ __forceinline__ unsigned cvt_pk(float lo, float hi) { unsigned r; asm volatile("v_cvt_pk_bf16_f32 %0, %1, %2" : "=v"(r) : "v"(lo), "v"(hi)); return r; }
; __device__ __forceinline__ void gmlp_phase(const Params& p, LAS unsigned char* lds, int G) {
;     ...
;             __syncthreads();
;             f32x16 acc0, acc1;
; #pragma unroll
;             for (int e = 0; e < 16; ++e) { acc0[e] = 0.f; acc1[e] = 0.f; }
;             const LAS bf16_t* bp0 = vT + (64 * wc + l32) * 136 + 8 * hi; const LAS bf16_t* bp1 = bp0 + 32 * 136;
; #pragma unroll
;             for (int ks = 0; ks < 8; ++ks) {
;                 const bf16x8 b0 = *(const LAS bf16x8*)(bp0 + 16 * ks), b1 = *(const LAS bf16x8*)(bp1 + 16 * ks);
;                 acc0 = __builtin_amdgcn_mfma_f32_32x32x16_bf16(b0, wf[ks], acc0, 0, 0, 0);
;                 acc1 = __builtin_amdgcn_mfma_f32_32x32x16_bf16(b1, wf[ks], acc1, 0, 0, 0);
;             }
;             float yss = 0.f;
; #pragma unroll
;             for (int q = 0; q < 4; ++q) {
; #pragma unroll
;                 for (int hb = 0; hb < 2; ++hb) {
;                     const int c = cb + 32 * hb + 8 * q;
;                     const u32x2 gu = guv[2 * q + hb]; const f32x4 gv = *(const f32x4*)(gvn + c);
;                     const float a0 = hb ? acc1[4 * q] : acc0[4 * q], a1 = hb ? acc1[4 * q + 1] : acc0[4 * q + 1], a2 = hb ? acc1[4 * q + 2] : acc0[4 * q + 2], a3 = hb ? acc1[4 * q + 3] : acc0[4 * q + 3];
;                     const float y0 = bflo(gu.x) * (gv.x * a0 + bi), y1 = bfhi(gu.x) * (gv.y * a1 + bi), y2 = bflo(gu.y) * (gv.z * a2 + bi), y3 = bfhi(gu.y) * (gv.w * a3 + bi);
;                     yss += (y0 * y0 + y1 * y1) + (y2 * y2 + y3 * y3);
;                     u32x2 o; o.x = cvt_pk(y0, y1); o.y = cvt_pk(y2, y3);
;                     *(u32x2*)(Y + tok * 1024 + c) = o;
.LBB0_658:
	s_waitcnt lgkmcnt(0)
	s_barrier
	ds_read_b128 v[4:7], v134
	ds_read_b128 v[122:125], v134 offset:32
	s_waitcnt vmcnt(8)
	v_lshlrev_b32_e32 v101, 16, v120
	s_waitcnt lgkmcnt(1)
	v_mfma_f32_32x32x16_bf16 v[16:31], v[4:7], v[0:3], 0
	ds_read_b128 v[4:7], v134 offset:8704
	s_waitcnt lgkmcnt(1)
	v_mfma_f32_32x32x16_bf16 v[16:31], v[122:125], v[60:63], v[16:31]
	ds_read_b128 v[122:125], v134 offset:8736
	s_waitcnt lgkmcnt(1)
	v_mfma_f32_32x32x16_bf16 v[0:15], v[4:7], v[0:3], 0
	s_waitcnt lgkmcnt(0)
	v_mfma_f32_32x32x16_bf16 v[0:15], v[122:125], v[60:63], v[0:15]
	global_load_dwordx4 v[122:125], v[90:91], off offset:1536
	ds_read_b128 v[60:63], v134 offset:64
	s_waitcnt lgkmcnt(0)
	v_mfma_f32_32x32x16_bf16 v[16:31], v[60:63], v[72:75], v[16:31]
	ds_read_b128 v[60:63], v134 offset:8768
	s_waitcnt lgkmcnt(0)
	v_mfma_f32_32x32x16_bf16 v[0:15], v[60:63], v[72:75], v[0:15]
	ds_read_b128 v[60:63], v134 offset:96
	s_waitcnt lgkmcnt(0)
	v_mfma_f32_32x32x16_bf16 v[16:31], v[60:63], v[68:71], v[16:31]
	ds_read_b128 v[60:63], v134 offset:8800
	s_waitcnt lgkmcnt(0)
	v_mfma_f32_32x32x16_bf16 v[0:15], v[60:63], v[68:71], v[0:15]
	ds_read_b128 v[60:63], v134 offset:128
	s_waitcnt lgkmcnt(0)
	v_mfma_f32_32x32x16_bf16 v[16:31], v[60:63], v[64:67], v[16:31]
	ds_read_b128 v[60:63], v134 offset:160
	s_waitcnt lgkmcnt(0)
	v_mfma_f32_32x32x16_bf16 v[16:31], v[60:63], v[56:59], v[16:31]
	ds_read_b128 v[60:63], v134 offset:192
	s_waitcnt lgkmcnt(0)
	v_mfma_f32_32x32x16_bf16 v[16:31], v[60:63], v[52:55], v[16:31]
	ds_read_b128 v[60:63], v134 offset:224
	ds_read_b128 v[68:71], v134 offset:8832
	s_waitcnt lgkmcnt(0)
	v_mfma_f32_32x32x16_bf16 v[0:15], v[68:71], v[64:67], v[0:15]
	v_mfma_f32_32x32x16_bf16 v[16:31], v[60:63], v[48:51], v[16:31]
	v_lshlrev_b64 v[60:61], 11, v[104:105]
	v_lshl_add_u64 v[104:105], s[12:13], 0, v[60:61]
	ds_read_b128 v[60:63], v134 offset:8864
	ds_read_b128 v[72:75], v134 offset:8896
	ds_read_b128 v[126:129], v134 offset:8928
	s_waitcnt vmcnt(0)
	s_nop 5
	v_fma_f32 v16, v16, v122, v97
	s_waitcnt lgkmcnt(2)
	v_mfma_f32_32x32x16_bf16 v[0:15], v[60:63], v[56:59], v[0:15]
	v_mul_f32_e32 v64, v16, v101
	v_and_b32_e32 v16, 0xffff0000, v120
	v_fma_f32 v17, v17, v123, v97
	v_mul_f32_e32 v65, v17, v16
	v_lshlrev_b32_e32 v16, 16, v121
	v_fma_f32 v17, v18, v124, v97
	v_mul_f32_e32 v66, v17, v16
	v_and_b32_e32 v16, 0xffff0000, v121
	v_fma_f32 v17, v19, v125, v97
	v_mul_f32_e32 v56, v17, v16
	v_lshl_add_u64 v[16:17], v[104:105], 0, v[76:77]
	v_cvt_pk_bf16_f32 v18, v64, v65
	v_cvt_pk_bf16_f32 v19, v66, v56
	ds_write_b64 v140, v[18:19] offset:0
	s_waitcnt lgkmcnt(1)
	v_mfma_f32_32x32x16_bf16 v[0:15], v[72:75], v[52:55], v[0:15]
	global_load_dwordx4 v[52:55], v[90:91], off offset:1664
	v_lshlrev_b32_e32 v18, 16, v118
	v_and_b32_e32 v19, 0xffff0000, v118
	v_lshlrev_b32_e32 v57, 16, v119
	v_and_b32_e32 v58, 0xffff0000, v119
	s_waitcnt lgkmcnt(0)
	v_mfma_f32_32x32x16_bf16 v[0:15], v[126:129], v[48:51], v[0:15]
	v_lshlrev_b32_e32 v50, 16, v116
	v_and_b32_e32 v51, 0xffff0000, v116
	s_waitcnt vmcnt(0)
	s_nop 8
	v_fma_f32 v0, v0, v52, v97
	v_fma_f32 v1, v1, v53, v97
	v_fma_f32 v2, v2, v54, v97
	v_fma_f32 v3, v3, v55, v97
	v_mul_f32_e32 v18, v0, v18
	v_mul_f32_e32 v19, v1, v19
	v_mul_f32_e32 v48, v2, v57
	v_mul_f32_e32 v49, v3, v58
	v_cvt_pk_bf16_f32 v0, v18, v19
	v_cvt_pk_bf16_f32 v1, v48, v49
	ds_write_b64 v140, v[0:1] offset:64
	global_load_dwordx4 v[0:3], v[90:91], off offset:1568
	v_lshlrev_b32_e32 v52, 16, v117
	v_and_b32_e32 v53, 0xffff0000, v117
	v_mul_f32_e32 v19, v19, v19
	v_mul_f32_e32 v49, v49, v49
	v_mul_f32_e32 v54, v65, v65
	v_mul_f32_e32 v55, v56, v56
	v_fmac_f32_e32 v19, v18, v18
	v_fmac_f32_e32 v49, v48, v48
	v_fmac_f32_e32 v54, v64, v64
	v_fmac_f32_e32 v55, v66, v66
	v_add_f32_e32 v18, v19, v49
	v_add_f32_e32 v54, v54, v55
	v_add_f32_e32 v18, v54, v18
	s_waitcnt vmcnt(0)
	v_fma_f32 v0, v20, v0, v97
	v_fma_f32 v1, v21, v1, v97
	v_fma_f32 v2, v22, v2, v97
	v_fma_f32 v3, v23, v3, v97
	v_mul_f32_e32 v20, v0, v50
	v_mul_f32_e32 v21, v1, v51
	v_mul_f32_e32 v22, v2, v52
	v_mul_f32_e32 v23, v3, v53
	v_cvt_pk_bf16_f32 v0, v20, v21
	v_cvt_pk_bf16_f32 v1, v22, v23
	ds_write_b64 v140, v[0:1] offset:16
	global_load_dwordx4 v[0:3], v[90:91], off offset:1696
	v_lshlrev_b32_e32 v50, 16, v114
	v_and_b32_e32 v51, 0xffff0000, v114
	v_lshlrev_b32_e32 v52, 16, v115
	v_and_b32_e32 v53, 0xffff0000, v115
	v_mul_f32_e32 v19, v21, v21
	v_mul_f32_e32 v21, v23, v23
	v_fmac_f32_e32 v19, v20, v20
	v_fmac_f32_e32 v21, v22, v22
	v_add_f32_e32 v19, v19, v21
	v_add_f32_e32 v18, v18, v19
	s_waitcnt vmcnt(0)
; __device__ __forceinline__ unsigned cvt_pk(float lo, float hi) { unsigned r; asm volatile("v_cvt_pk_bf16_f32 %0, %1, %2" : "=v"(r) : "v"(lo), "v"(hi)); return r; }
; __device__ __forceinline__ void gmlp_phase(const Params& p, LAS unsigned char* lds, int G) {
;     ...
;             float yss = 0.f;
; #pragma unroll
;             for (int q = 0; q < 4; ++q) {
; #pragma unroll
;                 for (int hb = 0; hb < 2; ++hb) {
;                     const int c = cb + 32 * hb + 8 * q;
;                     const u32x2 gu = guv[2 * q + hb]; const f32x4 gv = *(const f32x4*)(gvn + c);
;                     const float a0 = hb ? acc1[4 * q] : acc0[4 * q], a1 = hb ? acc1[4 * q + 1] : acc0[4 * q + 1], a2 = hb ? acc1[4 * q + 2] : acc0[4 * q + 2], a3 = hb ? acc1[4 * q + 3] : acc0[4 * q + 3];
;                     const float y0 = bflo(gu.x) * (gv.x * a0 + bi), y1 = bfhi(gu.x) * (gv.y * a1 + bi), y2 = bflo(gu.y) * (gv.z * a2 + bi), y3 = bfhi(gu.y) * (gv.w * a3 + bi);
;                     yss += (y0 * y0 + y1 * y1) + (y2 * y2 + y3 * y3);
;                     u32x2 o; o.x = cvt_pk(y0, y1); o.y = cvt_pk(y2, y3);
;                     *(u32x2*)(Y + tok * 1024 + c) = o;
;                 }
;             }
;             yss += __shfl_xor(yss, 32);
;             if (hi == 0) unsafeAtomicAdd(SSA + tok, yss);
	v_fma_f32 v0, v4, v0, v97
	v_fma_f32 v1, v5, v1, v97
	v_fma_f32 v2, v6, v2, v97
	v_fma_f32 v3, v7, v3, v97
	v_mul_f32_e32 v4, v0, v50
	v_mul_f32_e32 v5, v1, v51
	v_mul_f32_e32 v6, v2, v52
	v_mul_f32_e32 v7, v3, v53
	v_cvt_pk_bf16_f32 v0, v4, v5
	v_cvt_pk_bf16_f32 v1, v6, v7
	ds_write_b64 v140, v[0:1] offset:80
	global_load_dwordx4 v[0:3], v[90:91], off offset:1600
	v_lshlrev_b32_e32 v50, 16, v112
	v_and_b32_e32 v51, 0xffff0000, v112
	v_lshlrev_b32_e32 v52, 16, v113
	v_and_b32_e32 v53, 0xffff0000, v113
	v_mul_f32_e32 v5, v5, v5
	v_mul_f32_e32 v7, v7, v7
	v_fmac_f32_e32 v5, v4, v4
	v_fmac_f32_e32 v7, v6, v6
	v_add_f32_e32 v4, v5, v7
	v_add_f32_e32 v4, v18, v4
	s_waitcnt vmcnt(0)
	v_fma_f32 v0, v24, v0, v97
	v_fma_f32 v1, v25, v1, v97
	v_fma_f32 v2, v26, v2, v97
	v_fma_f32 v3, v27, v3, v97
	v_mul_f32_e32 v24, v0, v50
	v_mul_f32_e32 v25, v1, v51
	v_mul_f32_e32 v26, v2, v52
	v_mul_f32_e32 v27, v3, v53
	v_cvt_pk_bf16_f32 v0, v24, v25
	v_cvt_pk_bf16_f32 v1, v26, v27
	ds_write_b64 v140, v[0:1] offset:32
	global_load_dwordx4 v[0:3], v[90:91], off offset:1728
	v_lshlrev_b32_e32 v50, 16, v110
	v_and_b32_e32 v51, 0xffff0000, v110
	v_lshlrev_b32_e32 v52, 16, v111
	v_and_b32_e32 v53, 0xffff0000, v111
	v_mul_f32_e32 v5, v25, v25
	v_mul_f32_e32 v6, v27, v27
	v_fmac_f32_e32 v5, v24, v24
	v_fmac_f32_e32 v6, v26, v26
	v_add_f32_e32 v5, v5, v6
	v_add_f32_e32 v4, v4, v5
	s_waitcnt vmcnt(0)
	v_fma_f32 v0, v8, v0, v97
	v_fma_f32 v1, v9, v1, v97
	v_fma_f32 v2, v10, v2, v97
	v_fma_f32 v3, v11, v3, v97
	v_mul_f32_e32 v8, v0, v50
	v_mul_f32_e32 v9, v1, v51
	v_mul_f32_e32 v10, v2, v52
	v_mul_f32_e32 v11, v3, v53
	v_cvt_pk_bf16_f32 v0, v8, v9
	v_cvt_pk_bf16_f32 v1, v10, v11
	ds_write_b64 v140, v[0:1] offset:96
	global_load_dwordx4 v[0:3], v[90:91], off offset:1632
	v_lshlrev_b32_e32 v50, 16, v108
	v_and_b32_e32 v51, 0xffff0000, v108
	v_lshlrev_b32_e32 v52, 16, v109
	v_and_b32_e32 v53, 0xffff0000, v109
	v_mul_f32_e32 v5, v9, v9
	v_mul_f32_e32 v6, v11, v11
	v_fmac_f32_e32 v5, v8, v8
	v_fmac_f32_e32 v6, v10, v10
	v_add_f32_e32 v5, v5, v6
	v_add_f32_e32 v4, v4, v5
	s_waitcnt vmcnt(0)
	v_fma_f32 v0, v28, v0, v97
	v_fma_f32 v1, v29, v1, v97
	v_fma_f32 v2, v30, v2, v97
	v_fma_f32 v3, v31, v3, v97
	v_mul_f32_e32 v28, v0, v50
	v_mul_f32_e32 v29, v1, v51
	v_mul_f32_e32 v30, v2, v52
	v_mul_f32_e32 v31, v3, v53
	v_cvt_pk_bf16_f32 v0, v28, v29
	v_cvt_pk_bf16_f32 v1, v30, v31
	ds_write_b64 v140, v[0:1] offset:48
	global_load_dwordx4 v[0:3], v[90:91], off offset:1760
	v_mul_f32_e32 v5, v29, v29
	v_mul_f32_e32 v6, v31, v31
	v_fmac_f32_e32 v5, v28, v28
	v_fmac_f32_e32 v6, v30, v30
	v_and_b32_e32 v51, 0xffff0000, v106
	v_and_b32_e32 v53, 0xffff0000, v107
	v_add_f32_e32 v5, v5, v6
	v_lshlrev_b32_e32 v50, 16, v106
	v_lshlrev_b32_e32 v52, 16, v107
	v_add_f32_e32 v4, v4, v5
	s_waitcnt vmcnt(0)
	v_fma_f32 v0, v12, v0, v97
	v_fma_f32 v1, v13, v1, v97
	v_fma_f32 v2, v14, v2, v97
	v_fmac_f32_e32 v97, v15, v3
	v_mul_f32_e32 v5, v1, v51
	v_mul_f32_e32 v7, v97, v53
	v_mul_f32_e32 v3, v0, v50
	v_mul_f32_e32 v6, v2, v52
	v_mul_f32_e32 v0, v5, v5
	v_mul_f32_e32 v1, v7, v7
	v_fmac_f32_e32 v0, v3, v3
	v_fmac_f32_e32 v1, v6, v6
	v_add_f32_e32 v0, v0, v1
	v_add_f32_e32 v0, v4, v0
	ds_bpermute_b32 v1, v169, v0
	v_cvt_pk_bf16_f32 v2, v3, v5
	v_cvt_pk_bf16_f32 v3, v6, v7
	ds_write_b64 v140, v[2:3] offset:112
	s_waitcnt lgkmcnt(0)
	ds_read_b128 v[148:151], v141 offset:0
	ds_read_b128 v[152:155], v141 offset:1152
	ds_read_b128 v[156:159], v141 offset:2304
	ds_read_b128 v[160:163], v141 offset:3456
	v_lshl_add_u64 v[164:165], v[16:17], 0, v[180:181]
	v_lshl_add_u64 v[170:171], v[16:17], 0, v[182:183]
	v_lshl_add_u64 v[172:173], v[16:17], 0, v[184:185]
	v_lshl_add_u64 v[174:175], v[16:17], 0, v[186:187]
	s_waitcnt lgkmcnt(0)
	global_store_dwordx4 v[164:165], v[148:151], off offset:768
	global_store_dwordx4 v[170:171], v[152:155], off offset:768
	global_store_dwordx4 v[172:173], v[156:159], off offset:768
	global_store_dwordx4 v[174:175], v[160:163], off offset:768
	s_and_saveexec_b64 s[34:35], s[38:39]
	s_cbranch_execz .LBB0_651
	s_waitcnt lgkmcnt(0)
	v_add_f32_e32 v0, v0, v1
	global_atomic_add_f32 v[102:103], v0, off
	s_branch .LBB0_651
